# c34 + P8 first half-tile: five gate-b load pairs widened to dwordx4 (spare quads, inverse lane-group exchange + v_mov after the half-tile's vmcnt(0))
# speedup vs baseline: 1.0236x; 1.0002x over previous
;     __device__ __forceinline__ void operator()(f32x4 (&acc)[2][2][4][2], const Unit& u, int wr, int wc, int fr, int fq) const {
;         const int row0 = u.pm * BM + wr * 64 + fr, cin = wc * 32 + 4 * fq, col0 = u.pn * BM + cin;
;         const size_t gofs = (size_t)(u.pn >> 1) * slab_elems + (u.pn & 1) * 256 + cin;
; #pragma unroll
;         for (int ai = 0; ai < 2; ++ai) {
;             unsigned long long wbv[4][2][2], wav[4][2][2];
; #pragma unroll
;             for (int m = 0; m < 4; ++m) { const size_t gro = gofs + (size_t)(row0 + ai * HALF + m * 16) * 512;
; #pragma unroll
;                 for (int bj = 0; bj < 2; ++bj)
; #pragma unroll
;                     for (int n = 0; n < 2; ++n) { wbv[m][bj][n] = *(const unsigned long long*)(gb + gro + bj * HALF + 16 * n);
;                         if (u.kh == 0) wav[m][bj][n] = __builtin_nontemporal_load((const unsigned long long*)(ga + gro + bj * HALF + 16 * n)); else wav[m][bj][n] = 0ull; } }
.LBB0_913:
	s_lshl_b32 s21, s4, 8
	s_ashr_i32 s4, s4, 1
	v_lshl_add_u32 v144, s6, 8, v223
	s_ashr_i32 s5, s4, 31
	s_and_b32 s6, s21, 0x100
	s_lshl_b64 s[4:5], s[4:5], 24
	v_or_b32_e32 v1, s6, v225
	v_ashrrev_i32_e32 v145, 31, v144
	v_or_b32_e32 v146, s4, v1
	v_mov_b32_e32 v147, s5
	v_lshlrev_b64 v[2:3], 9, v[144:145]
	v_lshl_add_u64 v[2:3], v[146:147], 0, v[2:3]
	v_lshlrev_b64 v[148:149], 1, v[2:3]
	v_lshl_add_u64 v[2:3], s[12:13], 0, v[148:149]
	v_and_b32_e32 v250, 48, v254
	v_mov_b32_e32 v251, 0
	v_lshrrev_b32_e32 v250, 1, v250
	v_lshl_add_u64 v[252:253], v[2:3], 0, v[250:251]
	global_load_dwordx4 v[230:233], v[252:253], off
	s_cmp_eq_u32 s3, 0
	s_cselect_b64 s[4:5], -1, 0
	s_cmp_lg_u32 s3, 0
	s_cselect_b64 s[38:39], -1, 0
	v_lshl_add_u64 v[148:149], s[10:11], 0, v[148:149]
	v_mov_b64_e32 v[210:211], 0
	s_and_b64 vcc, exec, s[38:39]
	v_mov_b64_e32 v[216:217], 0
	s_cbranch_vccnz .LBB0_915
	global_load_dwordx2 v[216:217], v[148:149], off nt
.LBB0_915:
	v_cndmask_b32_e64 v1, 0, 1, s[4:5]
	v_cmp_ne_u32_e64 s[6:7], 1, v1
	s_andn2_b64 vcc, exec, s[4:5]
	s_cbranch_vccnz .LBB0_917
	global_load_dwordx2 v[210:211], v[148:149], off offset:32 nt
.LBB0_917:
	v_lshl_add_u64 v[252:253], v[2:3], 0, v[250:251]
	global_load_dwordx4 v[234:237], v[252:253], off offset:256
	v_mov_b64_e32 v[202:203], 0
	s_and_b64 vcc, exec, s[6:7]
	v_mov_b64_e32 v[206:207], 0
	s_cbranch_vccz .LBB0_1078
	s_and_b64 vcc, exec, s[6:7]
	s_cbranch_vccz .LBB0_1079
.LBB0_919:
	v_or_b32_e32 v200, 16, v144
	v_ashrrev_i32_e32 v201, 31, v200
	v_lshlrev_b64 v[2:3], 9, v[200:201]
	v_lshl_add_u64 v[2:3], v[2:3], 0, v[146:147]
	v_lshlrev_b64 v[2:3], 1, v[2:3]
	v_lshl_add_u64 v[148:149], s[12:13], 0, v[2:3]
	v_lshl_add_u64 v[252:253], v[148:149], 0, v[250:251]
	global_load_dwordx4 v[238:241], v[252:253], off
	v_lshl_add_u64 v[2:3], s[10:11], 0, v[2:3]
	v_mov_b64_e32 v[192:193], 0
	s_and_b64 vcc, exec, s[6:7]
	v_mov_b64_e32 v[196:197], 0
	s_cbranch_vccz .LBB0_1080
	s_and_b64 vcc, exec, s[6:7]
	s_cbranch_vccz .LBB0_1081
.LBB0_921:
	v_lshl_add_u64 v[252:253], v[148:149], 0, v[250:251]
	global_load_dwordx4 v[242:245], v[252:253], off offset:256
	v_mov_b64_e32 v[184:185], 0
	s_and_b64 vcc, exec, s[6:7]
	v_mov_b64_e32 v[188:189], 0
	s_cbranch_vccz .LBB0_1082
	s_and_b64 vcc, exec, s[6:7]
	s_cbranch_vccz .LBB0_1083
.LBB0_923:
	v_or_b32_e32 v182, 32, v144
	v_ashrrev_i32_e32 v183, 31, v182
	v_lshlrev_b64 v[2:3], 9, v[182:183]
	v_lshl_add_u64 v[2:3], v[2:3], 0, v[146:147]
	v_lshlrev_b64 v[2:3], 1, v[2:3]
	v_lshl_add_u64 v[148:149], s[12:13], 0, v[2:3]
	v_lshl_add_u64 v[252:253], v[148:149], 0, v[250:251]
	global_load_dwordx4 v[246:249], v[252:253], off
	v_lshl_add_u64 v[2:3], s[10:11], 0, v[2:3]
	v_mov_b64_e32 v[174:175], 0
	s_and_b64 vcc, exec, s[6:7]
	v_mov_b64_e32 v[178:179], 0
	s_cbranch_vccz .LBB0_1084
	s_and_b64 vcc, exec, s[6:7]
	s_cbranch_vccz .LBB0_1085

; __device__ __forceinline__ unsigned cvt_pk_bf16(float lo, float hi) { unsigned r; asm volatile("v_cvt_pk_bf16_f32 %0, %1, %2" : "=v"(r) : "v"(lo), "v"(hi)); return r; }
;     __device__ __forceinline__ void operator()(f32x4 (&acc)[2][2][4][2], const Unit& u, int wr, int wc, int fr, int fq) const {
;     ...
;             asm volatile("" ::: "memory");
; #pragma unroll
;             for (int m = 0; m < 4; ++m) { const size_t off = (size_t)(row0 + ai * HALF + m * 16) * 1024 + col0;
; #pragma unroll
;                 for (int bj = 0; bj < 2; ++bj)
; #pragma unroll
;                     for (int n = 0; n < 2; ++n) {
;                         const unsigned long long wb = wbv[m][bj][n];
;                         f32x4 eb;
;                         eb[0] = __expf(-fmaxf(__uint_as_float((unsigned)(wb & 0xffffull) << 16), -60.f)); eb[1] = __expf(-fmaxf(__uint_as_float((unsigned)((wb >> 16) & 0xffffull) << 16), -60.f));
;                         eb[2] = __expf(-fmaxf(__uint_as_float((unsigned)((wb >> 32) & 0xffffull) << 16), -60.f)); eb[3] = __expf(-fmaxf(__uint_as_float((unsigned)((wb >> 48) & 0xffffull) << 16), -60.f));
;                         if (u.kh == 0) {
;                             const unsigned long long wa = wav[m][bj][n];
;                             f32x4 ea;
;                             ea[0] = __expf(-__uint_as_float((unsigned)(wa & 0xffffull) << 16)); ea[1] = __expf(-__uint_as_float((unsigned)((wa >> 16) & 0xffffull) << 16));
;                             ea[2] = __expf(-__uint_as_float((unsigned)((wa >> 32) & 0xffffull) << 16)); ea[3] = __expf(-__uint_as_float((unsigned)((wa >> 48) & 0xffffull) << 16));
; #pragma unroll
;                             for (int e_ = 0; e_ < 4; ++e_) acc[ai][bj][m][n][e_] *= (1.0f + eb[e_]) * __builtin_amdgcn_rcpf(1.0f + ea[e_]);
;                         } else {
;                             f32x4 o;
; #pragma unroll
;                             for (int e_ = 0; e_ < 4; ++e_) o[e_] = acc[ai][bj][m][n][e_] * __builtin_amdgcn_rcpf(1.0f + eb[e_]);
;                             *(unsigned long long*)(merged + off + bj * HALF + 16 * n) = (unsigned long long)cvt_pk_bf16(o[0], o[1]) | ((unsigned long long)cvt_pk_bf16(o[2], o[3]) << 32);
.LBB0_931:
	s_waitcnt vmcnt(0)
	v_permlane16_swap_b32_e32 v230, v232
	v_permlane16_swap_b32_e32 v231, v233
	v_permlane16_swap_b32_e32 v234, v236
	v_permlane16_swap_b32_e32 v235, v237
	v_permlane16_swap_b32_e32 v238, v240
	v_permlane16_swap_b32_e32 v239, v241
	v_permlane16_swap_b32_e32 v242, v244
	v_permlane16_swap_b32_e32 v243, v245
	v_permlane16_swap_b32_e32 v246, v248
	v_permlane16_swap_b32_e32 v247, v249
	s_nop 0
	v_permlane32_swap_b32_e32 v230, v232
	v_permlane32_swap_b32_e32 v231, v233
	v_permlane32_swap_b32_e32 v234, v236
	v_permlane32_swap_b32_e32 v235, v237
	v_permlane32_swap_b32_e32 v238, v240
	v_permlane32_swap_b32_e32 v239, v241
	v_permlane32_swap_b32_e32 v242, v244
	v_permlane32_swap_b32_e32 v243, v245
	v_permlane32_swap_b32_e32 v246, v248
	v_permlane32_swap_b32_e32 v247, v249
	s_nop 0
	v_mov_b32_e32 v212, v230
	v_mov_b32_e32 v213, v231
	v_mov_b32_e32 v214, v232
	v_mov_b32_e32 v215, v233
	v_mov_b32_e32 v208, v234
	v_mov_b32_e32 v209, v235
	v_mov_b32_e32 v204, v236
	v_mov_b32_e32 v205, v237
	v_mov_b32_e32 v198, v238
	v_mov_b32_e32 v199, v239
	v_mov_b32_e32 v194, v240
	v_mov_b32_e32 v195, v241
	v_mov_b32_e32 v190, v242
	v_mov_b32_e32 v191, v243
	v_mov_b32_e32 v186, v244
	v_mov_b32_e32 v187, v245
	v_mov_b32_e32 v180, v246
	v_mov_b32_e32 v181, v247
	v_mov_b32_e32 v176, v248
	v_mov_b32_e32 v177, v249
	v_lshlrev_b32_e32 v1, 16, v212
	v_max_f32_e32 v1, v1, v1
	v_max_f32_e32 v1, 0xc2700000, v1
	v_mul_f32_e32 v1, 0xbfb8aa3b, v1
	v_exp_f32_e32 v218, v1
	v_and_b32_e32 v1, 0xffff0000, v212
	v_max_f32_e32 v1, v1, v1
	v_max_f32_e32 v1, 0xc2700000, v1
	v_mul_f32_e32 v1, 0xbfb8aa3b, v1
	v_exp_f32_e32 v219, v1
	v_alignbit_b32 v1, v213, v212, 16
	v_and_b32_e32 v1, 0xffff0000, v1
	v_max_f32_e32 v1, v1, v1
	v_max_f32_e32 v1, 0xc2700000, v1
	v_mul_f32_e32 v1, 0xbfb8aa3b, v1
	v_exp_f32_e32 v220, v1
	v_and_b32_e32 v1, 0xffff0000, v213
	v_max_f32_e32 v1, v1, v1
	v_max_f32_e32 v1, 0xc2700000, v1
	v_mul_f32_e32 v1, 0xbfb8aa3b, v1
	v_exp_f32_e32 v221, v1
	v_or_b32_e32 v2, s21, v225
	v_lshlrev_b64 v[228:229], 11, v[144:145]
	v_ashrrev_i32_e32 v3, 31, v2
	v_cndmask_b32_e64 v1, 0, 1, s[38:39]
	v_lshl_add_u64 v[212:213], s[14:15], 0, v[228:229]
	s_mov_b64 s[42:43], -1
	v_cmp_ne_u32_e64 s[4:5], 1, v1
	s_andn2_b64 vcc, exec, s[38:39]
	v_lshl_add_u64 v[212:213], v[2:3], 1, v[212:213]
	s_cbranch_vccnz .LBB0_933
	v_add_f32_e32 v1, 1.0, v218
	v_add_f32_e32 v145, 1.0, v219
	v_add_f32_e32 v222, 1.0, v220
	v_add_f32_e32 v227, 1.0, v221
	v_rcp_f32_e32 v1, v1
	v_rcp_f32_e32 v145, v145
	v_rcp_f32_e32 v222, v222
	v_rcp_f32_e32 v227, v227
	s_mov_b64 s[42:43], 0
	v_mul_f32_e32 v1, v128, v1
	v_mul_f32_e32 v145, v129, v145
	v_mul_f32_e32 v222, v130, v222
	v_mul_f32_e32 v227, v131, v227
	v_cvt_pk_bf16_f32 v228, v1, v145
	v_cvt_pk_bf16_f32 v229, v222, v227
	v_and_b32_e32 v244, 48, v254
	v_mov_b32_e32 v245, 0
	v_lshrrev_b32_e32 v244, 1, v244
	v_mov_b32_e32 v240, v228
	v_mov_b32_e32 v241, v229
